# attention: next-tile K/V prefetch address math + loads moved under the K ds_read latency (skip-path copy for inactive waves)
# baseline (speedup 1.0000x reference)
.Latt_sk4:
	s_or_b64 exec, exec, s[44:45]
	v_add_u32_e32 v128, s5, v14
	v_add_u32_e32 v188, s5, v15
	v_min_u32_e32 v128, 0x80ff, v128
	v_add_u32_e32 v190, 1, v188
	v_min_u32_e32 v188, 0x80ff, v188
	v_min_u32_e32 v190, 0x80ff, v190
	v_lshl_add_u32 v130, v128, 12, v238
	v_lshl_add_u32 v132, v128, 6, v239
	v_lshl_add_u32 v188, v188, 12, v174
	v_lshl_add_u32 v190, v190, 12, v174
	global_load_dwordx4 v[128:131], v130, s[98:99]
	s_nop 0
	global_load_dwordx4 v[132:135], v132, s[100:101]
	global_load_dwordx2 v[188:189], v188, s[98:99] offset:128
	global_load_dwordx2 v[190:191], v190, s[98:99] offset:128
	s_branch .LBB0_462
.Latt_sk3:
	s_or_b64 exec, exec, s[46:47]
	v_add_u32_e32 v120, s5, v14
	v_add_u32_e32 v184, s5, v15
	v_min_u32_e32 v120, 0x80ff, v120
	v_add_u32_e32 v186, 1, v184
	v_min_u32_e32 v184, 0x80ff, v184
	v_min_u32_e32 v186, 0x80ff, v186
	v_lshl_add_u32 v122, v120, 12, v238
	v_lshl_add_u32 v124, v120, 6, v239
	v_lshl_add_u32 v184, v184, 12, v174
	v_lshl_add_u32 v186, v186, 12, v174
	global_load_dwordx4 v[120:123], v122, s[98:99]
	s_nop 0
	global_load_dwordx4 v[124:127], v124, s[100:101]
	global_load_dwordx2 v[184:185], v184, s[98:99] offset:128
	global_load_dwordx2 v[186:187], v186, s[98:99] offset:128
	s_branch .LBB0_451
.Latt_sk2:
	s_or_b64 exec, exec, s[44:45]
	v_min_u32_e32 v120, 0x80ff, v120
	v_add_u32_e32 v186, 1, v184
	v_min_u32_e32 v184, 0x80ff, v184
	v_min_u32_e32 v186, 0x80ff, v186
	v_lshl_add_u32 v122, v120, 12, v238
	v_lshl_add_u32 v124, v120, 6, v239
	v_lshl_add_u32 v184, v184, 12, v174
	v_lshl_add_u32 v186, v186, 12, v174
	global_load_dwordx4 v[120:123], v122, s[98:99]
	s_nop 0
	global_load_dwordx4 v[124:127], v124, s[100:101]
	global_load_dwordx2 v[184:185], v184, s[98:99] offset:128
	global_load_dwordx2 v[186:187], v186, s[98:99] offset:128
	s_branch .LBB0_437
.Latt_sk1:
	s_or_b64 exec, exec, s[46:47]
	s_waitcnt vmcnt(3)
	v_add_u32_e32 v2, s5, v221
	v_add_u32_e32 v14, s5, v222
	v_min_u32_e32 v2, 0x80ff, v2
	v_add_u32_e32 v192, 1, v14
	v_min_u32_e32 v14, 0x80ff, v14
	v_min_u32_e32 v192, 0x80ff, v192
	v_lshl_add_u32 v4, v2, 12, v238
	s_waitcnt vmcnt(2)
	v_lshl_add_u32 v6, v2, 6, v239
	v_lshl_add_u32 v14, v14, 12, v174
	v_lshl_add_u32 v192, v192, 12, v174
	global_load_dwordx4 v[2:5], v4, s[98:99]
	s_nop 0
	global_load_dwordx4 v[6:9], v6, s[100:101]
	global_load_dwordx2 v[14:15], v14, s[98:99] offset:128
	global_load_dwordx2 v[192:193], v192, s[98:99] offset:128
	s_branch .LBB0_426

; #define LAS __attribute__((address_space(3)))
; __device__ __forceinline__ void qk_tile(f32x16& s0, f32x16& s1, LAS unsigned char* kb, const bf16x8 (&qr)[6], const f32x16& negm, int r32, int hi) {
;     bf16x8 kf[12];
; #pragma unroll
;     for (int ks = 0; ks < 6; ++ks) { kf[2 * ks] = *(const LAS bf16x8*)(kb + r32 * KPT + ks * 32 + hi * 16); kf[2 * ks + 1] = *(const LAS bf16x8*)(kb + (32 + r32) * KPT + ks * 32 + hi * 16); }
;     __builtin_amdgcn_sched_barrier(0);
; #pragma unroll
;     for (int ks = 0; ks < 6; ++ks) {
;         s0 = __builtin_amdgcn_mfma_f32_32x32x16_bf16(kf[2 * ks], qr[ks], ks == 0 ? negm : s0, 0, 0, 0);
;         s1 = __builtin_amdgcn_mfma_f32_32x32x16_bf16(kf[2 * ks + 1], qr[ks], ks == 0 ? negm : s1, 0, 0, 0);
;     }
; }
; __device__ __forceinline__ void sm_pv(f32x16& s0, f32x16& s1, f32x16& o0, f32x16& o1, float& m_run, float& l_run, f32x16& negm, LAS unsigned char* vb, bool domask, int kbase, int qm, int r32, int hi) {
;     s16x4 vlo[8], vhh[8];
; #pragma unroll
;     for (int kk = 0; kk < 4; ++kk) { const int koff = 2 * (16 * kk + 4 * hi);
;         vlo[2 * kk] = *(const LAS s16x4*)(vb + r32 * VP + koff); vhh[2 * kk] = *(const LAS s16x4*)(vb + r32 * VP + koff + 16);
;         vlo[2 * kk + 1] = *(const LAS s16x4*)(vb + (32 + r32) * VP + koff); vhh[2 * kk + 1] = *(const LAS s16x4*)(vb + (32 + r32) * VP + koff + 16); }
;     __builtin_amdgcn_sched_barrier(0);
;     if (domask) {
;         const int kb0 = kbase + 4 * hi;
; #pragma unroll
;         for (int r = 0; r < 16; ++r) { const int kv = kb0 + (r & 3) + 8 * (r >> 2); if (kv > qm) s0[r] = -INFINITY; if (kv + 32 > qm) s1[r] = -INFINITY; }
;     }
.LBB0_418:
	s_add_i32 s85, s84, -3
	s_cmp_lt_u32 s85, s57
	s_cselect_b64 s[44:45], -1, 0
	s_and_b64 s[4:5], s[44:45], exec
	s_cselect_b32 s4, 0, s79
	s_lshl_b32 s4, s4, 6
	v_add_u32_e32 v221, s83, v213
	v_add_u32_e32 v222, s83, v173
	s_sub_i32 s5, 0x80, s4
	v_cmp_le_u32_e32 vcc, s83, v220
	s_and_saveexec_b64 s[46:47], vcc
	s_cbranch_execz .Latt_sk1
	ds_read_b128 v[10:13], v240 offset:13312
	ds_read_b128 v[136:139], v240 offset:13344
	ds_read_b128 v[140:143], v240 offset:19968
	ds_read_b128 v[144:147], v240 offset:20000
	ds_read_b128 v[148:151], v240 offset:13376
	ds_read_b128 v[152:155], v240 offset:13408
	ds_read_b128 v[156:159], v240 offset:20032
	ds_read_b128 v[160:163], v240 offset:20064
	ds_read_b128 v[224:227], v240 offset:13440
	ds_read_b128 v[228:231], v240 offset:13472
	ds_read_b128 v[232:235], v240 offset:20096
	ds_read_b128 v[246:249], v240 offset:20128
	s_waitcnt vmcnt(3)
	v_add_u32_e32 v2, s5, v221
	v_add_u32_e32 v14, s5, v222
	v_min_u32_e32 v2, 0x80ff, v2
	v_add_u32_e32 v192, 1, v14
	v_min_u32_e32 v14, 0x80ff, v14
	v_min_u32_e32 v192, 0x80ff, v192
	v_lshl_add_u32 v4, v2, 12, v238
	s_waitcnt vmcnt(2)
	v_lshl_add_u32 v6, v2, 6, v239
	v_lshl_add_u32 v14, v14, 12, v174
	v_lshl_add_u32 v192, v192, 12, v174
	global_load_dwordx4 v[2:5], v4, s[98:99]
	s_nop 0
	global_load_dwordx4 v[6:9], v6, s[100:101]
	global_load_dwordx2 v[14:15], v14, s[98:99] offset:128
	global_load_dwordx2 v[192:193], v192, s[98:99] offset:128
	s_waitcnt lgkmcnt(11)
	v_mfma_f32_32x32x16_bf16 v[80:95], v[10:13], v[96:99], v[48:63]
	s_add_i32 s4, s83, 63
	v_cmp_gt_i32_e32 vcc, s4, v175
	s_waitcnt lgkmcnt(9)
	v_mfma_f32_32x32x16_bf16 v[64:79], v[140:143], v[96:99], v[48:63]
	v_mfma_f32_32x32x16_bf16 v[80:95], v[136:139], v[100:103], v[80:95]
	s_waitcnt lgkmcnt(8)
	v_mfma_f32_32x32x16_bf16 v[64:79], v[144:147], v[100:103], v[64:79]
	s_waitcnt lgkmcnt(7)
	v_mfma_f32_32x32x16_bf16 v[80:95], v[148:151], v[104:107], v[80:95]
	s_waitcnt lgkmcnt(5)
	v_mfma_f32_32x32x16_bf16 v[64:79], v[156:159], v[104:107], v[64:79]
	v_mfma_f32_32x32x16_bf16 v[80:95], v[152:155], v[108:111], v[80:95]
	ds_read2_b64 v[152:155], v250 offset0:68 offset1:70
	s_waitcnt lgkmcnt(5)
	v_mfma_f32_32x32x16_bf16 v[64:79], v[160:163], v[108:111], v[64:79]
	ds_read2_b64 v[160:163], v250 offset0:64 offset1:66
	ds_read2_b64 v[156:159], v251 offset0:96 offset1:98
	ds_read2_b64 v[148:151], v251 offset0:100 offset1:102
	ds_read2_b64 v[144:147], v250 offset0:72 offset1:74
	ds_read2_b64 v[140:143], v251 offset0:104 offset1:106
	ds_read2_b64 v[136:139], v250 offset0:76 offset1:78
	ds_read2_b64 v[10:13], v251 offset0:108 offset1:110
	s_waitcnt lgkmcnt(11)
	v_mfma_f32_32x32x16_bf16 v[80:95], v[224:227], v[112:115], v[80:95]
	s_waitcnt lgkmcnt(9)
	v_mfma_f32_32x32x16_bf16 v[64:79], v[232:235], v[112:115], v[64:79]
	v_mfma_f32_32x32x16_bf16 v[80:95], v[228:231], v[116:119], v[80:95]
	s_waitcnt lgkmcnt(8)
	v_mfma_f32_32x32x16_bf16 v[64:79], v[246:249], v[116:119], v[64:79]
	s_and_saveexec_b64 s[58:59], vcc
	s_cbranch_execz .LBB0_423
	v_add_u32_e32 v223, s83, v201
	v_add_u32_e32 v224, 32, v223
	v_cmp_ge_i32_e64 s[4:5], v177, v224
	v_add_u32_e32 v224, 33, v223
	v_cmp_ge_i32_e64 s[6:7], v177, v224
	v_add_u32_e32 v224, 2, v223
	v_cmp_le_u32_e32 vcc, v223, v219
	s_nop 2
	v_cndmask_b32_e64 v65, v244, v65, s[6:7]
	v_cmp_ge_i32_e64 s[6:7], v177, v224
	v_add_u32_e32 v224, 34, v223
	v_cmp_ge_i32_e64 s[8:9], v177, v224
	v_add_u32_e32 v224, 3, v223
	v_cndmask_b32_e64 v64, v244, v64, s[4:5]
	v_cndmask_b32_e64 v66, v244, v66, s[8:9]
	v_cmp_ge_i32_e64 s[8:9], v177, v224
	v_add_u32_e32 v224, 35, v223
	v_cmp_ge_i32_e64 s[10:11], v177, v224
	v_add_u32_e32 v224, 8, v223
	v_cmp_gt_i32_e64 s[4:5], v177, v223
	v_cndmask_b32_e64 v67, v244, v67, s[10:11]
	v_cmp_ge_i32_e64 s[10:11], v177, v224
	v_add_u32_e32 v224, 40, v223
	v_cmp_ge_i32_e64 s[12:13], v177, v224
	v_add_u32_e32 v224, 9, v223
	s_nop 0
	v_cndmask_b32_e64 v68, v244, v68, s[12:13]
	v_cmp_ge_i32_e64 s[12:13], v177, v224
	v_add_u32_e32 v224, 41, v223
	v_cmp_ge_i32_e64 s[14:15], v177, v224
	v_add_u32_e32 v224, 10, v223
	s_nop 0
	v_cndmask_b32_e64 v69, v244, v69, s[14:15]
	v_cmp_ge_i32_e64 s[14:15], v177, v224
	v_add_u32_e32 v224, 42, v223
	v_cmp_ge_i32_e64 s[16:17], v177, v224
	v_add_u32_e32 v224, 11, v223
	s_nop 0
	v_cndmask_b32_e64 v70, v244, v70, s[16:17]
	v_cmp_ge_i32_e64 s[16:17], v177, v224
	v_add_u32_e32 v224, 43, v223
	v_cmp_ge_i32_e64 s[18:19], v177, v224
	v_add_u32_e32 v224, 16, v223
	s_nop 0
	v_cndmask_b32_e64 v71, v244, v71, s[18:19]
	v_cmp_ge_i32_e64 s[18:19], v177, v224
	v_add_u32_e32 v224, 48, v223
	v_cmp_ge_i32_e64 s[20:21], v177, v224
	v_add_u32_e32 v224, 17, v223
	s_nop 0
	v_cndmask_b32_e64 v72, v244, v72, s[20:21]
	v_cmp_ge_i32_e64 s[20:21], v177, v224
	v_add_u32_e32 v224, 49, v223
	v_cmp_ge_i32_e64 s[22:23], v177, v224
	v_add_u32_e32 v224, 18, v223
	s_nop 0
	v_cndmask_b32_e64 v73, v244, v73, s[22:23]
	v_cmp_ge_i32_e64 s[22:23], v177, v224
	v_add_u32_e32 v224, 50, v223
	v_cmp_ge_i32_e64 s[24:25], v177, v224
	v_add_u32_e32 v224, 19, v223
	s_nop 0
	v_cndmask_b32_e64 v74, v244, v74, s[24:25]
	v_cmp_ge_i32_e64 s[24:25], v177, v224
	v_add_u32_e32 v224, 51, v223
	v_cmp_ge_i32_e64 s[26:27], v177, v224
	v_add_u32_e32 v224, 24, v223
	s_nop 0
	v_cndmask_b32_e64 v75, v244, v75, s[26:27]
	v_cmp_ge_i32_e64 s[26:27], v177, v224
	v_add_u32_e32 v224, 56, v223
	v_cmp_ge_i32_e64 s[28:29], v177, v224
	v_add_u32_e32 v224, 25, v223
	s_nop 0
	v_cndmask_b32_e64 v76, v244, v76, s[28:29]
	v_cmp_ge_i32_e64 s[28:29], v177, v224
	v_add_u32_e32 v224, 57, v223
	v_cmp_ge_i32_e64 s[30:31], v177, v224
	v_add_u32_e32 v224, 26, v223
	s_nop 0
	v_cndmask_b32_e64 v77, v244, v77, s[30:31]
	v_cmp_ge_i32_e64 s[30:31], v177, v224
	v_add_u32_e32 v224, 58, v223
	v_cmp_ge_i32_e64 s[34:35], v177, v224
	v_add_u32_e32 v224, 27, v223
	v_add_u32_e32 v223, 59, v223
	v_cndmask_b32_e64 v78, v244, v78, s[34:35]
	v_cmp_ge_i32_e64 s[34:35], v177, v224
	v_cmp_lt_i32_e64 s[36:37], v177, v223
	s_and_saveexec_b64 s[40:41], s[36:37]
	v_mov_b32_e32 v79, s52
	s_or_b64 exec, exec, s[40:41]
	v_cndmask_b32_e32 v80, v244, v80, vcc
	v_cndmask_b32_e64 v81, v244, v81, s[4:5]
	v_cndmask_b32_e64 v82, v244, v82, s[6:7]
	v_cndmask_b32_e64 v83, v244, v83, s[8:9]
	v_cndmask_b32_e64 v84, v244, v84, s[10:11]
	v_cndmask_b32_e64 v85, v244, v85, s[12:13]
	v_cndmask_b32_e64 v86, v244, v86, s[14:15]
	v_cndmask_b32_e64 v87, v244, v87, s[16:17]
	v_cndmask_b32_e64 v88, v244, v88, s[18:19]
	v_cndmask_b32_e64 v89, v244, v89, s[20:21]
	v_cndmask_b32_e64 v90, v244, v90, s[22:23]
	v_cndmask_b32_e64 v91, v244, v91, s[24:25]
	v_cndmask_b32_e64 v92, v244, v92, s[26:27]
	v_cndmask_b32_e64 v93, v244, v93, s[28:29]
	v_cndmask_b32_e64 v94, v244, v94, s[30:31]
	v_cndmask_b32_e64 v95, v244, v95, s[34:35]

; #define LAS __attribute__((address_space(3)))
; __device__ __forceinline__ void qk_tile(f32x16& s0, f32x16& s1, LAS unsigned char* kb, const bf16x8 (&qr)[6], const f32x16& negm, int r32, int hi) {
;     bf16x8 kf[12];
; #pragma unroll
;     for (int ks = 0; ks < 6; ++ks) { kf[2 * ks] = *(const LAS bf16x8*)(kb + r32 * KPT + ks * 32 + hi * 16); kf[2 * ks + 1] = *(const LAS bf16x8*)(kb + (32 + r32) * KPT + ks * 32 + hi * 16); }
;     __builtin_amdgcn_sched_barrier(0);
; #pragma unroll
;     for (int ks = 0; ks < 6; ++ks) {
;         s0 = __builtin_amdgcn_mfma_f32_32x32x16_bf16(kf[2 * ks], qr[ks], ks == 0 ? negm : s0, 0, 0, 0);
;         s1 = __builtin_amdgcn_mfma_f32_32x32x16_bf16(kf[2 * ks + 1], qr[ks], ks == 0 ? negm : s1, 0, 0, 0);
;     }
; }
.LBB0_426:
	s_or_b64 exec, exec, s[46:47]
	ds_write_b128 v210, v[120:123]
	s_and_saveexec_b64 s[4:5], s[2:3]
	ds_write_b128 v210, v[124:127] offset:128
	s_or_b64 exec, exec, s[4:5]
	s_waitcnt vmcnt(4)
	v_perm_b32 v10, v186, v184, s94
	v_perm_b32 v11, v186, v184, s95
	ds_write2_b32 v214, v10, v11 offset1:34
	v_perm_b32 v10, v187, v185, s94
	v_perm_b32 v11, v187, v185, s95
	ds_write2_b32 v214, v10, v11 offset0:68 offset1:102
	s_waitcnt lgkmcnt(0)
	s_barrier
	s_andn2_b64 vcc, exec, s[44:45]
	s_cbranch_vccnz .LBB0_417
	s_cmp_gt_u32 s84, s57
	s_cselect_b32 s4, s79, 0
	s_lshl_b32 s4, s4, 6
	s_sub_i32 s5, 0xc0, s4
	v_add_u32_e32 v120, s5, v221
	v_add_u32_e32 v184, s5, v222
	s_add_i32 s4, s83, 64
	v_cmp_le_u32_e32 vcc, s4, v220
	s_and_saveexec_b64 s[44:45], vcc
	s_cbranch_execz .Latt_sk2
	ds_read_b128 v[10:13], v241
	ds_read_b128 v[136:139], v241 offset:32
	ds_read_b128 v[140:143], v241 offset:6656
	ds_read_b128 v[144:147], v241 offset:6688
	ds_read_b128 v[148:151], v241 offset:64
	ds_read_b128 v[152:155], v241 offset:96
	ds_read_b128 v[156:159], v241 offset:6720
	ds_read_b128 v[160:163], v241 offset:6752
	ds_read_b128 v[222:225], v241 offset:128
	ds_read_b128 v[226:229], v241 offset:160
	ds_read_b128 v[230:233], v241 offset:6784
	ds_read_b128 v[234:237], v241 offset:6816
	v_min_u32_e32 v120, 0x80ff, v120
	v_add_u32_e32 v186, 1, v184
	v_min_u32_e32 v184, 0x80ff, v184
	v_min_u32_e32 v186, 0x80ff, v186
	v_lshl_add_u32 v122, v120, 12, v238
	v_lshl_add_u32 v124, v120, 6, v239
	v_lshl_add_u32 v184, v184, 12, v174
	v_lshl_add_u32 v186, v186, 12, v174
	global_load_dwordx4 v[120:123], v122, s[98:99]
	s_nop 0
	global_load_dwordx4 v[124:127], v124, s[100:101]
	global_load_dwordx2 v[184:185], v184, s[98:99] offset:128
	global_load_dwordx2 v[186:187], v186, s[98:99] offset:128
	s_waitcnt lgkmcnt(11)
	v_mfma_f32_32x32x16_bf16 v[80:95], v[10:13], v[96:99], v[48:63]
	s_add_i32 s4, s83, 0x7f
	v_cmp_gt_i32_e32 vcc, s4, v175
	s_waitcnt lgkmcnt(9)
	v_mfma_f32_32x32x16_bf16 v[64:79], v[140:143], v[96:99], v[48:63]
	v_mfma_f32_32x32x16_bf16 v[80:95], v[136:139], v[100:103], v[80:95]
	s_waitcnt lgkmcnt(8)
	v_mfma_f32_32x32x16_bf16 v[64:79], v[144:147], v[100:103], v[64:79]
	s_waitcnt lgkmcnt(7)
	v_mfma_f32_32x32x16_bf16 v[80:95], v[148:151], v[104:107], v[80:95]
	s_waitcnt lgkmcnt(5)
	v_mfma_f32_32x32x16_bf16 v[64:79], v[156:159], v[104:107], v[64:79]
	v_mfma_f32_32x32x16_bf16 v[80:95], v[152:155], v[108:111], v[80:95]
	ds_read2_b64 v[152:155], v252 offset0:4 offset1:6
	s_waitcnt lgkmcnt(5)
	v_mfma_f32_32x32x16_bf16 v[64:79], v[160:163], v[108:111], v[64:79]
	ds_read2_b64 v[160:163], v252 offset1:2
	ds_read2_b64 v[156:159], v253 offset0:32 offset1:34
	ds_read2_b64 v[148:151], v253 offset0:36 offset1:38
	ds_read2_b64 v[144:147], v252 offset0:8 offset1:10
	ds_read2_b64 v[140:143], v253 offset0:40 offset1:42
	ds_read2_b64 v[136:139], v252 offset0:12 offset1:14
	ds_read2_b64 v[10:13], v253 offset0:44 offset1:46
	s_waitcnt lgkmcnt(11)
	v_mfma_f32_32x32x16_bf16 v[80:95], v[222:225], v[112:115], v[80:95]
	s_waitcnt lgkmcnt(9)
	v_mfma_f32_32x32x16_bf16 v[64:79], v[230:233], v[112:115], v[64:79]
	v_mfma_f32_32x32x16_bf16 v[80:95], v[226:229], v[116:119], v[80:95]
	s_waitcnt lgkmcnt(8)
	v_mfma_f32_32x32x16_bf16 v[64:79], v[234:237], v[116:119], v[64:79]
	s_and_saveexec_b64 s[46:47], vcc
	s_cbranch_execz .LBB0_434
; __device__ __forceinline__ void sm_pv(f32x16& s0, f32x16& s1, f32x16& o0, f32x16& o1, float& m_run, float& l_run, f32x16& negm, LAS unsigned char* vb, bool domask, int kbase, int qm, int r32, int hi) {
;     ...
;     if (domask) {
;         const int kb0 = kbase + 4 * hi;
; #pragma unroll
;         for (int r = 0; r < 16; ++r) { const int kv = kb0 + (r & 3) + 8 * (r >> 2); if (kv > qm) s0[r] = -INFINITY; if (kv + 32 > qm) s1[r] = -INFINITY; }
;     }
	v_add_u32_e32 v221, s83, v201
	v_add_u32_e32 v223, 0x60, v221
	v_add_u32_e32 v222, 64, v221
	v_cmp_le_u32_e64 s[4:5], v223, v219
	v_cmp_le_u32_e32 vcc, v222, v219
	s_nop 4
	v_cndmask_b32_e64 v64, v244, v64, s[4:5]
	v_cmp_lt_u32_e64 s[4:5], v222, v219
	v_add_u32_e32 v222, 0x61, v221
	v_cmp_le_u32_e64 s[6:7], v222, v219
	v_add_u32_e32 v222, 0x42, v221
	s_nop 0
	v_cndmask_b32_e64 v65, v244, v65, s[6:7]
	v_cmp_le_u32_e64 s[6:7], v222, v219
	v_add_u32_e32 v222, 0x62, v221
	v_cmp_le_u32_e64 s[8:9], v222, v219
	v_add_u32_e32 v222, 0x43, v221
	s_nop 0
	v_cndmask_b32_e64 v66, v244, v66, s[8:9]
	v_cmp_le_u32_e64 s[8:9], v222, v219
	v_add_u32_e32 v222, 0x63, v221
	v_cmp_le_u32_e64 s[10:11], v222, v219
	v_add_u32_e32 v222, 0x48, v221
	s_nop 0
	v_cndmask_b32_e64 v67, v244, v67, s[10:11]
	v_cmp_le_u32_e64 s[10:11], v222, v219
	v_add_u32_e32 v222, 0x68, v221
	v_cmp_le_u32_e64 s[12:13], v222, v219
	v_add_u32_e32 v222, 0x49, v221
	s_nop 0
	v_cndmask_b32_e64 v68, v244, v68, s[12:13]
	v_cmp_le_u32_e64 s[12:13], v222, v219
	v_add_u32_e32 v222, 0x69, v221
	v_cmp_le_u32_e64 s[14:15], v222, v219
	v_add_u32_e32 v222, 0x4a, v221
	s_nop 0
	v_cndmask_b32_e64 v69, v244, v69, s[14:15]
	v_cmp_le_u32_e64 s[14:15], v222, v219
	v_add_u32_e32 v222, 0x6a, v221
	v_cmp_le_u32_e64 s[16:17], v222, v219
	v_add_u32_e32 v222, 0x4b, v221
	s_nop 0
	v_cndmask_b32_e64 v70, v244, v70, s[16:17]
	v_cmp_le_u32_e64 s[16:17], v222, v219
	v_add_u32_e32 v222, 0x6b, v221
	v_cmp_le_u32_e64 s[18:19], v222, v219
	v_add_u32_e32 v222, 0x50, v221
	s_nop 0
	v_cndmask_b32_e64 v71, v244, v71, s[18:19]
	v_cmp_le_u32_e64 s[18:19], v222, v219
	v_add_u32_e32 v222, 0x70, v221
	v_cmp_le_u32_e64 s[20:21], v222, v219
	v_add_u32_e32 v222, 0x51, v221
	s_nop 0
	v_cndmask_b32_e64 v72, v244, v72, s[20:21]
	v_cmp_le_u32_e64 s[20:21], v222, v219
	v_add_u32_e32 v222, 0x71, v221
	v_cmp_le_u32_e64 s[22:23], v222, v219
	v_add_u32_e32 v222, 0x52, v221
	s_nop 0
	v_cndmask_b32_e64 v73, v244, v73, s[22:23]
	v_cmp_le_u32_e64 s[22:23], v222, v219
	v_add_u32_e32 v222, 0x72, v221
	v_cmp_le_u32_e64 s[24:25], v222, v219
	v_add_u32_e32 v222, 0x53, v221
	s_nop 0
	v_cndmask_b32_e64 v74, v244, v74, s[24:25]
	v_cmp_le_u32_e64 s[24:25], v222, v219
	v_add_u32_e32 v222, 0x73, v221
	v_cmp_le_u32_e64 s[26:27], v222, v219
	v_add_u32_e32 v222, 0x58, v221
	s_nop 0
	v_cndmask_b32_e64 v75, v244, v75, s[26:27]
	v_cmp_le_u32_e64 s[26:27], v222, v219
	v_add_u32_e32 v222, 0x78, v221
	v_cmp_le_u32_e64 s[28:29], v222, v219
	v_add_u32_e32 v222, 0x59, v221
	s_nop 0
	v_cndmask_b32_e64 v76, v244, v76, s[28:29]
	v_cmp_le_u32_e64 s[28:29], v222, v219
	v_add_u32_e32 v222, 0x79, v221
	v_cmp_le_u32_e64 s[30:31], v222, v219
	v_add_u32_e32 v222, 0x5a, v221
	s_nop 0
	v_cndmask_b32_e64 v77, v244, v77, s[30:31]
	v_cmp_le_u32_e64 s[30:31], v222, v219
	v_add_u32_e32 v222, 0x7a, v221
	v_cmp_le_u32_e64 s[34:35], v222, v219
	v_add_u32_e32 v222, 0x5b, v221
	v_add_u32_e32 v221, 0x7b, v221
	v_cndmask_b32_e64 v78, v244, v78, s[34:35]
	v_cmp_le_u32_e64 s[34:35], v222, v219
	v_cmp_gt_u32_e64 s[36:37], v221, v219
	s_and_saveexec_b64 s[40:41], s[36:37]
	v_mov_b32_e32 v79, s52
	s_or_b64 exec, exec, s[40:41]
	v_cndmask_b32_e64 v81, v244, v81, s[4:5]
	v_cndmask_b32_e32 v80, v244, v80, vcc
	v_cndmask_b32_e64 v82, v244, v82, s[6:7]
	v_cndmask_b32_e64 v83, v244, v83, s[8:9]
	v_cndmask_b32_e64 v84, v244, v84, s[10:11]
	v_cndmask_b32_e64 v85, v244, v85, s[12:13]
	v_cndmask_b32_e64 v86, v244, v86, s[14:15]
	v_cndmask_b32_e64 v87, v244, v87, s[16:17]
	v_cndmask_b32_e64 v88, v244, v88, s[18:19]
	v_cndmask_b32_e64 v89, v244, v89, s[20:21]
	v_cndmask_b32_e64 v90, v244, v90, s[22:23]
	v_cndmask_b32_e64 v91, v244, v91, s[24:25]
	v_cndmask_b32_e64 v92, v244, v92, s[26:27]
	v_cndmask_b32_e64 v93, v244, v93, s[28:29]
	v_cndmask_b32_e64 v94, v244, v94, s[30:31]
	v_cndmask_b32_e64 v95, v244, v95, s[34:35]

; #define LAS __attribute__((address_space(3)))
; __device__ __forceinline__ void qk_tile(f32x16& s0, f32x16& s1, LAS unsigned char* kb, const bf16x8 (&qr)[6], const f32x16& negm, int r32, int hi) {
;     bf16x8 kf[12];
; #pragma unroll
;     for (int ks = 0; ks < 6; ++ks) { kf[2 * ks] = *(const LAS bf16x8*)(kb + r32 * KPT + ks * 32 + hi * 16); kf[2 * ks + 1] = *(const LAS bf16x8*)(kb + (32 + r32) * KPT + ks * 32 + hi * 16); }
;     __builtin_amdgcn_sched_barrier(0);
; #pragma unroll
;     for (int ks = 0; ks < 6; ++ks) {
;         s0 = __builtin_amdgcn_mfma_f32_32x32x16_bf16(kf[2 * ks], qr[ks], ks == 0 ? negm : s0, 0, 0, 0);
;         s1 = __builtin_amdgcn_mfma_f32_32x32x16_bf16(kf[2 * ks + 1], qr[ks], ks == 0 ? negm : s1, 0, 0, 0);
;     }
; }
; __device__ __forceinline__ void sm_pv(f32x16& s0, f32x16& s1, f32x16& o0, f32x16& o1, float& m_run, float& l_run, f32x16& negm, LAS unsigned char* vb, bool domask, int kbase, int qm, int r32, int hi) {
;     s16x4 vlo[8], vhh[8];
; #pragma unroll
;     for (int kk = 0; kk < 4; ++kk) { const int koff = 2 * (16 * kk + 4 * hi);
;         vlo[2 * kk] = *(const LAS s16x4*)(vb + r32 * VP + koff); vhh[2 * kk] = *(const LAS s16x4*)(vb + r32 * VP + koff + 16);
;         vlo[2 * kk + 1] = *(const LAS s16x4*)(vb + (32 + r32) * VP + koff); vhh[2 * kk + 1] = *(const LAS s16x4*)(vb + (32 + r32) * VP + koff + 16); }
;     __builtin_amdgcn_sched_barrier(0);
;     if (domask) {
;         const int kb0 = kbase + 4 * hi;
; #pragma unroll
;         for (int r = 0; r < 16; ++r) { const int kv = kb0 + (r & 3) + 8 * (r >> 2); if (kv > qm) s0[r] = -INFINITY; if (kv + 32 > qm) s1[r] = -INFINITY; }
;     }
.LBB0_443:
	s_add_i32 s85, s84, -3
	s_cmp_lt_u32 s85, s57
	s_cselect_b64 s[44:45], -1, 0
	s_and_b64 s[4:5], s[44:45], exec
	s_cselect_b32 s4, 0, s79
	s_lshl_b32 s4, s4, 6
	s_sub_i32 s5, 0x80, s4
	v_add_u32_e32 v14, s83, v213
	v_add_u32_e32 v15, s83, v173
	v_cmp_le_u32_e32 vcc, s83, v220
	s_and_saveexec_b64 s[46:47], vcc
	s_cbranch_execz .Latt_sk3
	ds_read_b128 v[2:5], v241
	ds_read_b128 v[6:9], v241 offset:32
	ds_read_b128 v[10:13], v241 offset:6656
	ds_read_b128 v[136:139], v241 offset:6688
	ds_read_b128 v[140:143], v241 offset:64
	ds_read_b128 v[144:147], v241 offset:96
	ds_read_b128 v[148:151], v241 offset:6720
	ds_read_b128 v[152:155], v241 offset:6752
	ds_read_b128 v[156:159], v241 offset:128
	ds_read_b128 v[160:163], v241 offset:160
	ds_read_b128 v[222:225], v241 offset:6784
	ds_read_b128 v[226:229], v241 offset:6816
	v_add_u32_e32 v120, s5, v14
	v_add_u32_e32 v184, s5, v15
	v_min_u32_e32 v120, 0x80ff, v120
	v_add_u32_e32 v186, 1, v184
	v_min_u32_e32 v184, 0x80ff, v184
	v_min_u32_e32 v186, 0x80ff, v186
	v_lshl_add_u32 v122, v120, 12, v238
	v_lshl_add_u32 v124, v120, 6, v239
	v_lshl_add_u32 v184, v184, 12, v174
	v_lshl_add_u32 v186, v186, 12, v174
	global_load_dwordx4 v[120:123], v122, s[98:99]
	s_nop 0
	global_load_dwordx4 v[124:127], v124, s[100:101]
	global_load_dwordx2 v[184:185], v184, s[98:99] offset:128
	global_load_dwordx2 v[186:187], v186, s[98:99] offset:128
	s_waitcnt lgkmcnt(11)
	v_mfma_f32_32x32x16_bf16 v[80:95], v[2:5], v[96:99], v[48:63]
	s_add_i32 s4, s83, 63
	v_cmp_gt_i32_e32 vcc, s4, v175
	s_waitcnt lgkmcnt(9)
	v_mfma_f32_32x32x16_bf16 v[64:79], v[10:13], v[96:99], v[48:63]
	v_mfma_f32_32x32x16_bf16 v[80:95], v[6:9], v[100:103], v[80:95]
	s_waitcnt lgkmcnt(8)
	v_mfma_f32_32x32x16_bf16 v[64:79], v[136:139], v[100:103], v[64:79]
	s_waitcnt lgkmcnt(7)
	v_mfma_f32_32x32x16_bf16 v[80:95], v[140:143], v[104:107], v[80:95]
	s_waitcnt lgkmcnt(5)
	v_mfma_f32_32x32x16_bf16 v[64:79], v[148:151], v[104:107], v[64:79]
	v_mfma_f32_32x32x16_bf16 v[80:95], v[144:147], v[108:111], v[80:95]
	ds_read2_b64 v[144:147], v252 offset0:4 offset1:6
	s_waitcnt lgkmcnt(5)
	v_mfma_f32_32x32x16_bf16 v[64:79], v[152:155], v[108:111], v[64:79]
	ds_read2_b64 v[152:155], v252 offset1:2
	ds_read2_b64 v[148:151], v253 offset0:32 offset1:34
	ds_read2_b64 v[140:143], v253 offset0:36 offset1:38
	ds_read2_b64 v[136:139], v252 offset0:8 offset1:10
	ds_read2_b64 v[10:13], v253 offset0:40 offset1:42
	ds_read2_b64 v[6:9], v252 offset0:12 offset1:14
	ds_read2_b64 v[2:5], v253 offset0:44 offset1:46
	s_waitcnt lgkmcnt(11)
	v_mfma_f32_32x32x16_bf16 v[80:95], v[156:159], v[112:115], v[80:95]
	s_waitcnt lgkmcnt(9)
	v_mfma_f32_32x32x16_bf16 v[64:79], v[222:225], v[112:115], v[64:79]
	v_mfma_f32_32x32x16_bf16 v[80:95], v[160:163], v[116:119], v[80:95]
	s_waitcnt lgkmcnt(8)
	v_mfma_f32_32x32x16_bf16 v[64:79], v[226:229], v[116:119], v[64:79]
	s_and_saveexec_b64 s[58:59], vcc
	s_cbranch_execz .LBB0_448
	v_add_u32_e32 v156, s83, v201
	v_add_u32_e32 v157, 32, v156
	v_cmp_ge_i32_e64 s[4:5], v177, v157
	v_add_u32_e32 v157, 33, v156
	v_cmp_ge_i32_e64 s[6:7], v177, v157
	v_add_u32_e32 v157, 2, v156
	v_cmp_le_u32_e32 vcc, v156, v219
	s_nop 2
	v_cndmask_b32_e64 v65, v244, v65, s[6:7]
	v_cmp_ge_i32_e64 s[6:7], v177, v157
	v_add_u32_e32 v157, 34, v156
	v_cmp_ge_i32_e64 s[8:9], v177, v157
	v_add_u32_e32 v157, 3, v156
	v_cndmask_b32_e64 v64, v244, v64, s[4:5]
	v_cndmask_b32_e64 v66, v244, v66, s[8:9]
	v_cmp_ge_i32_e64 s[8:9], v177, v157
	v_add_u32_e32 v157, 35, v156
	v_cmp_ge_i32_e64 s[10:11], v177, v157
	v_add_u32_e32 v157, 8, v156
	v_cmp_gt_i32_e64 s[4:5], v177, v156
	v_cndmask_b32_e64 v67, v244, v67, s[10:11]
	v_cmp_ge_i32_e64 s[10:11], v177, v157
	v_add_u32_e32 v157, 40, v156
	v_cmp_ge_i32_e64 s[12:13], v177, v157
	v_add_u32_e32 v157, 9, v156
	s_nop 0
	v_cndmask_b32_e64 v68, v244, v68, s[12:13]
	v_cmp_ge_i32_e64 s[12:13], v177, v157
	v_add_u32_e32 v157, 41, v156
	v_cmp_ge_i32_e64 s[14:15], v177, v157
	v_add_u32_e32 v157, 10, v156
	s_nop 0
	v_cndmask_b32_e64 v69, v244, v69, s[14:15]
	v_cmp_ge_i32_e64 s[14:15], v177, v157
	v_add_u32_e32 v157, 42, v156
	v_cmp_ge_i32_e64 s[16:17], v177, v157
	v_add_u32_e32 v157, 11, v156
	s_nop 0
	v_cndmask_b32_e64 v70, v244, v70, s[16:17]
	v_cmp_ge_i32_e64 s[16:17], v177, v157
	v_add_u32_e32 v157, 43, v156
	v_cmp_ge_i32_e64 s[18:19], v177, v157
	v_add_u32_e32 v157, 16, v156
	s_nop 0
	v_cndmask_b32_e64 v71, v244, v71, s[18:19]
	v_cmp_ge_i32_e64 s[18:19], v177, v157
	v_add_u32_e32 v157, 48, v156
	v_cmp_ge_i32_e64 s[20:21], v177, v157
	v_add_u32_e32 v157, 17, v156
	s_nop 0
	v_cndmask_b32_e64 v72, v244, v72, s[20:21]
	v_cmp_ge_i32_e64 s[20:21], v177, v157
	v_add_u32_e32 v157, 49, v156
	v_cmp_ge_i32_e64 s[22:23], v177, v157
	v_add_u32_e32 v157, 18, v156
	s_nop 0
	v_cndmask_b32_e64 v73, v244, v73, s[22:23]
	v_cmp_ge_i32_e64 s[22:23], v177, v157
	v_add_u32_e32 v157, 50, v156
	v_cmp_ge_i32_e64 s[24:25], v177, v157
	v_add_u32_e32 v157, 19, v156
	s_nop 0
	v_cndmask_b32_e64 v74, v244, v74, s[24:25]
	v_cmp_ge_i32_e64 s[24:25], v177, v157
	v_add_u32_e32 v157, 51, v156
	v_cmp_ge_i32_e64 s[26:27], v177, v157
	v_add_u32_e32 v157, 24, v156
	s_nop 0
	v_cndmask_b32_e64 v75, v244, v75, s[26:27]
	v_cmp_ge_i32_e64 s[26:27], v177, v157
	v_add_u32_e32 v157, 56, v156
	v_cmp_ge_i32_e64 s[28:29], v177, v157
	v_add_u32_e32 v157, 25, v156
	s_nop 0
	v_cndmask_b32_e64 v76, v244, v76, s[28:29]
	v_cmp_ge_i32_e64 s[28:29], v177, v157
	v_add_u32_e32 v157, 57, v156
	v_cmp_ge_i32_e64 s[30:31], v177, v157
	v_add_u32_e32 v157, 26, v156
	s_nop 0
	v_cndmask_b32_e64 v77, v244, v77, s[30:31]
	v_cmp_ge_i32_e64 s[30:31], v177, v157
	v_add_u32_e32 v157, 58, v156
	v_cmp_ge_i32_e64 s[34:35], v177, v157
	v_add_u32_e32 v157, 27, v156
	v_add_u32_e32 v156, 59, v156
	v_cndmask_b32_e64 v78, v244, v78, s[34:35]
	v_cmp_ge_i32_e64 s[34:35], v177, v157
	v_cmp_lt_i32_e64 s[36:37], v177, v156
	s_and_saveexec_b64 s[40:41], s[36:37]
	v_mov_b32_e32 v79, s52
	s_or_b64 exec, exec, s[40:41]
	v_cndmask_b32_e32 v80, v244, v80, vcc
	v_cndmask_b32_e64 v81, v244, v81, s[4:5]
	v_cndmask_b32_e64 v82, v244, v82, s[6:7]
	v_cndmask_b32_e64 v83, v244, v83, s[8:9]
	v_cndmask_b32_e64 v84, v244, v84, s[10:11]
	v_cndmask_b32_e64 v85, v244, v85, s[12:13]
	v_cndmask_b32_e64 v86, v244, v86, s[14:15]
	v_cndmask_b32_e64 v87, v244, v87, s[16:17]
	v_cndmask_b32_e64 v88, v244, v88, s[18:19]
	v_cndmask_b32_e64 v89, v244, v89, s[20:21]
	v_cndmask_b32_e64 v90, v244, v90, s[22:23]
	v_cndmask_b32_e64 v91, v244, v91, s[24:25]
	v_cndmask_b32_e64 v92, v244, v92, s[26:27]
	v_cndmask_b32_e64 v93, v244, v93, s[28:29]
	v_cndmask_b32_e64 v94, v244, v94, s[30:31]
	v_cndmask_b32_e64 v95, v244, v95, s[34:35]

; #define LAS __attribute__((address_space(3)))
; __device__ __forceinline__ void qk_tile(f32x16& s0, f32x16& s1, LAS unsigned char* kb, const bf16x8 (&qr)[6], const f32x16& negm, int r32, int hi) {
;     bf16x8 kf[12];
; #pragma unroll
;     for (int ks = 0; ks < 6; ++ks) { kf[2 * ks] = *(const LAS bf16x8*)(kb + r32 * KPT + ks * 32 + hi * 16); kf[2 * ks + 1] = *(const LAS bf16x8*)(kb + (32 + r32) * KPT + ks * 32 + hi * 16); }
;     __builtin_amdgcn_sched_barrier(0);
; #pragma unroll
;     for (int ks = 0; ks < 6; ++ks) {
;         s0 = __builtin_amdgcn_mfma_f32_32x32x16_bf16(kf[2 * ks], qr[ks], ks == 0 ? negm : s0, 0, 0, 0);
;         s1 = __builtin_amdgcn_mfma_f32_32x32x16_bf16(kf[2 * ks + 1], qr[ks], ks == 0 ? negm : s1, 0, 0, 0);
;     }
; }
; __device__ __forceinline__ void sm_pv(f32x16& s0, f32x16& s1, f32x16& o0, f32x16& o1, float& m_run, float& l_run, f32x16& negm, LAS unsigned char* vb, bool domask, int kbase, int qm, int r32, int hi) {
;     s16x4 vlo[8], vhh[8];
; #pragma unroll
;     for (int kk = 0; kk < 4; ++kk) { const int koff = 2 * (16 * kk + 4 * hi);
;         vlo[2 * kk] = *(const LAS s16x4*)(vb + r32 * VP + koff); vhh[2 * kk] = *(const LAS s16x4*)(vb + r32 * VP + koff + 16);
;         vlo[2 * kk + 1] = *(const LAS s16x4*)(vb + (32 + r32) * VP + koff); vhh[2 * kk + 1] = *(const LAS s16x4*)(vb + (32 + r32) * VP + koff + 16); }
;     __builtin_amdgcn_sched_barrier(0);
;     if (domask) {
;         const int kb0 = kbase + 4 * hi;
; #pragma unroll
;         for (int r = 0; r < 16; ++r) { const int kv = kb0 + (r & 3) + 8 * (r >> 2); if (kv > qm) s0[r] = -INFINITY; if (kv + 32 > qm) s1[r] = -INFINITY; }
;     }
.LBB0_453:
	s_or_b64 exec, exec, s[4:5]
	s_waitcnt vmcnt(4)
	v_perm_b32 v2, v190, v188, s94
	v_perm_b32 v3, v190, v188, s95
	ds_write2_b32 v254, v2, v3 offset0:128 offset1:162
	v_perm_b32 v2, v191, v189, s94
	v_perm_b32 v3, v191, v189, s95
	ds_write2_b32 v254, v2, v3 offset0:196 offset1:230
	s_waitcnt lgkmcnt(0)
	s_barrier
	s_andn2_b64 vcc, exec, s[44:45]
	s_cbranch_vccnz .LBB0_442
	s_cmp_gt_u32 s84, s57
	s_cselect_b32 s4, s79, 0
	s_lshl_b32 s4, s4, 6
	s_sub_i32 s5, 0xc0, s4
	s_add_i32 s4, s83, 64
	v_cmp_le_u32_e32 vcc, s4, v220
	s_and_saveexec_b64 s[44:45], vcc
	s_cbranch_execz .Latt_sk4
	ds_read_b128 v[2:5], v240 offset:13312
	ds_read_b128 v[6:9], v240 offset:13344
	ds_read_b128 v[10:13], v240 offset:19968
	ds_read_b128 v[136:139], v240 offset:20000
	ds_read_b128 v[140:143], v240 offset:13376
	ds_read_b128 v[144:147], v240 offset:13408
	ds_read_b128 v[148:151], v240 offset:20032
	ds_read_b128 v[152:155], v240 offset:20064
	ds_read_b128 v[156:159], v240 offset:13440
	ds_read_b128 v[160:163], v240 offset:13472
	ds_read_b128 v[222:225], v240 offset:20096
	ds_read_b128 v[226:229], v240 offset:20128
	v_add_u32_e32 v128, s5, v14
	v_add_u32_e32 v188, s5, v15
	v_min_u32_e32 v128, 0x80ff, v128
	v_add_u32_e32 v190, 1, v188
	v_min_u32_e32 v188, 0x80ff, v188
	v_min_u32_e32 v190, 0x80ff, v190
	v_lshl_add_u32 v130, v128, 12, v238
	v_lshl_add_u32 v132, v128, 6, v239
	v_lshl_add_u32 v188, v188, 12, v174
	v_lshl_add_u32 v190, v190, 12, v174
	global_load_dwordx4 v[128:131], v130, s[98:99]
	s_nop 0
	global_load_dwordx4 v[132:135], v132, s[100:101]
	global_load_dwordx2 v[188:189], v188, s[98:99] offset:128
	global_load_dwordx2 v[190:191], v190, s[98:99] offset:128
	s_waitcnt lgkmcnt(11)
	v_mfma_f32_32x32x16_bf16 v[80:95], v[2:5], v[96:99], v[48:63]
	s_add_i32 s4, s83, 0x7f
	v_cmp_gt_i32_e32 vcc, s4, v175
	s_waitcnt lgkmcnt(9)
	v_mfma_f32_32x32x16_bf16 v[64:79], v[10:13], v[96:99], v[48:63]
	v_mfma_f32_32x32x16_bf16 v[80:95], v[6:9], v[100:103], v[80:95]
	s_waitcnt lgkmcnt(8)
	v_mfma_f32_32x32x16_bf16 v[64:79], v[136:139], v[100:103], v[64:79]
	s_waitcnt lgkmcnt(7)
	v_mfma_f32_32x32x16_bf16 v[80:95], v[140:143], v[104:107], v[80:95]
	s_waitcnt lgkmcnt(5)
	v_mfma_f32_32x32x16_bf16 v[64:79], v[148:151], v[104:107], v[64:79]
	v_mfma_f32_32x32x16_bf16 v[80:95], v[144:147], v[108:111], v[80:95]
	ds_read2_b64 v[144:147], v250 offset0:68 offset1:70
	s_waitcnt lgkmcnt(5)
	v_mfma_f32_32x32x16_bf16 v[64:79], v[152:155], v[108:111], v[64:79]
	ds_read2_b64 v[152:155], v250 offset0:64 offset1:66
	ds_read2_b64 v[148:151], v251 offset0:96 offset1:98
	ds_read2_b64 v[140:143], v251 offset0:100 offset1:102
	ds_read2_b64 v[136:139], v250 offset0:72 offset1:74
	ds_read2_b64 v[10:13], v251 offset0:104 offset1:106
	ds_read2_b64 v[6:9], v250 offset0:76 offset1:78
	ds_read2_b64 v[2:5], v251 offset0:108 offset1:110
	s_waitcnt lgkmcnt(11)
	v_mfma_f32_32x32x16_bf16 v[80:95], v[156:159], v[112:115], v[80:95]
	s_waitcnt lgkmcnt(9)
	v_mfma_f32_32x32x16_bf16 v[64:79], v[222:225], v[112:115], v[64:79]
	v_mfma_f32_32x32x16_bf16 v[80:95], v[160:163], v[116:119], v[80:95]
	s_waitcnt lgkmcnt(8)
	v_mfma_f32_32x32x16_bf16 v[64:79], v[226:229], v[116:119], v[64:79]
	s_and_saveexec_b64 s[46:47], vcc
	s_cbranch_execz .LBB0_459
	v_add_u32_e32 v14, s83, v201
	v_add_u32_e32 v156, 0x60, v14
	v_add_u32_e32 v15, 64, v14
	v_cmp_le_u32_e64 s[4:5], v156, v219
	v_cmp_le_u32_e32 vcc, v15, v219
	s_nop 4
	v_cndmask_b32_e64 v64, v244, v64, s[4:5]
	v_cmp_lt_u32_e64 s[4:5], v15, v219
	v_add_u32_e32 v15, 0x61, v14
	v_cmp_le_u32_e64 s[6:7], v15, v219
	v_add_u32_e32 v15, 0x42, v14
	s_nop 0
	v_cndmask_b32_e64 v65, v244, v65, s[6:7]
	v_cmp_le_u32_e64 s[6:7], v15, v219
	v_add_u32_e32 v15, 0x62, v14
	v_cmp_le_u32_e64 s[8:9], v15, v219
	v_add_u32_e32 v15, 0x43, v14
	s_nop 0
	v_cndmask_b32_e64 v66, v244, v66, s[8:9]
	v_cmp_le_u32_e64 s[8:9], v15, v219
	v_add_u32_e32 v15, 0x63, v14
	v_cmp_le_u32_e64 s[10:11], v15, v219
	v_add_u32_e32 v15, 0x48, v14
	s_nop 0
	v_cndmask_b32_e64 v67, v244, v67, s[10:11]
	v_cmp_le_u32_e64 s[10:11], v15, v219
	v_add_u32_e32 v15, 0x68, v14
	v_cmp_le_u32_e64 s[12:13], v15, v219
	v_add_u32_e32 v15, 0x49, v14
	s_nop 0
	v_cndmask_b32_e64 v68, v244, v68, s[12:13]
	v_cmp_le_u32_e64 s[12:13], v15, v219
	v_add_u32_e32 v15, 0x69, v14
	v_cmp_le_u32_e64 s[14:15], v15, v219
	v_add_u32_e32 v15, 0x4a, v14
	s_nop 0
	v_cndmask_b32_e64 v69, v244, v69, s[14:15]
	v_cmp_le_u32_e64 s[14:15], v15, v219
	v_add_u32_e32 v15, 0x6a, v14
	v_cmp_le_u32_e64 s[16:17], v15, v219
	v_add_u32_e32 v15, 0x4b, v14
	s_nop 0
	v_cndmask_b32_e64 v70, v244, v70, s[16:17]
	v_cmp_le_u32_e64 s[16:17], v15, v219
	v_add_u32_e32 v15, 0x6b, v14
	v_cmp_le_u32_e64 s[18:19], v15, v219
	v_add_u32_e32 v15, 0x50, v14
	s_nop 0
	v_cndmask_b32_e64 v71, v244, v71, s[18:19]
	v_cmp_le_u32_e64 s[18:19], v15, v219
	v_add_u32_e32 v15, 0x70, v14
	v_cmp_le_u32_e64 s[20:21], v15, v219
	v_add_u32_e32 v15, 0x51, v14
	s_nop 0
	v_cndmask_b32_e64 v72, v244, v72, s[20:21]
	v_cmp_le_u32_e64 s[20:21], v15, v219
	v_add_u32_e32 v15, 0x71, v14
	v_cmp_le_u32_e64 s[22:23], v15, v219
	v_add_u32_e32 v15, 0x52, v14
	s_nop 0
	v_cndmask_b32_e64 v73, v244, v73, s[22:23]
	v_cmp_le_u32_e64 s[22:23], v15, v219
	v_add_u32_e32 v15, 0x72, v14
	v_cmp_le_u32_e64 s[24:25], v15, v219
	v_add_u32_e32 v15, 0x53, v14
	s_nop 0
	v_cndmask_b32_e64 v74, v244, v74, s[24:25]
	v_cmp_le_u32_e64 s[24:25], v15, v219
	v_add_u32_e32 v15, 0x73, v14
	v_cmp_le_u32_e64 s[26:27], v15, v219
	v_add_u32_e32 v15, 0x58, v14
	s_nop 0
	v_cndmask_b32_e64 v75, v244, v75, s[26:27]
	v_cmp_le_u32_e64 s[26:27], v15, v219
	v_add_u32_e32 v15, 0x78, v14
	v_cmp_le_u32_e64 s[28:29], v15, v219
	v_add_u32_e32 v15, 0x59, v14
	s_nop 0
	v_cndmask_b32_e64 v76, v244, v76, s[28:29]
	v_cmp_le_u32_e64 s[28:29], v15, v219
	v_add_u32_e32 v15, 0x79, v14
	v_cmp_le_u32_e64 s[30:31], v15, v219
	v_add_u32_e32 v15, 0x5a, v14
	s_nop 0
	v_cndmask_b32_e64 v77, v244, v77, s[30:31]
	v_cmp_le_u32_e64 s[30:31], v15, v219
	v_add_u32_e32 v15, 0x7a, v14
	v_cmp_le_u32_e64 s[34:35], v15, v219
	v_add_u32_e32 v15, 0x5b, v14
	v_add_u32_e32 v14, 0x7b, v14
	v_cndmask_b32_e64 v78, v244, v78, s[34:35]
	v_cmp_le_u32_e64 s[34:35], v15, v219
	v_cmp_gt_u32_e64 s[36:37], v14, v219
	s_and_saveexec_b64 s[40:41], s[36:37]
	v_mov_b32_e32 v79, s52
	s_or_b64 exec, exec, s[40:41]
	v_cndmask_b32_e64 v81, v244, v81, s[4:5]
	v_cndmask_b32_e32 v80, v244, v80, vcc
	v_cndmask_b32_e64 v82, v244, v82, s[6:7]
	v_cndmask_b32_e64 v83, v244, v83, s[8:9]
	v_cndmask_b32_e64 v84, v244, v84, s[10:11]
	v_cndmask_b32_e64 v85, v244, v85, s[12:13]
	v_cndmask_b32_e64 v86, v244, v86, s[14:15]
	v_cndmask_b32_e64 v87, v244, v87, s[16:17]
	v_cndmask_b32_e64 v88, v244, v88, s[18:19]
	v_cndmask_b32_e64 v89, v244, v89, s[20:21]
	v_cndmask_b32_e64 v90, v244, v90, s[22:23]
	v_cndmask_b32_e64 v91, v244, v91, s[24:25]
	v_cndmask_b32_e64 v92, v244, v92, s[26:27]
	v_cndmask_b32_e64 v93, v244, v93, s[28:29]
	v_cndmask_b32_e64 v94, v244, v94, s[30:31]
	v_cndmask_b32_e64 v95, v244, v95, s[34:35]
